# P7 conv+silu epilogue rewritten: DPP-fused fmac taps on accumulators, weights loaded once, saddr addressing; plus spatial LDS staging and sc1 partial stores
# speedup vs baseline: 1.0351x; 1.0158x over previous
.LBB0_1187:
	v_readlane_b32 s12, v253, 21
	v_readlane_b32 s13, v253, 22
	v_readlane_b32 s18, v253, 27
	v_readlane_b32 s19, v253, 28
	v_readlane_b32 s20, v253, 29
	v_readlane_b32 s21, v253, 30
	v_readlane_b32 s22, v253, 31
	v_readlane_b32 s23, v253, 32
	v_readlane_b32 s24, v253, 33
	v_readlane_b32 s25, v253, 34
	v_readlane_b32 s26, v253, 35
	v_readlane_b32 s27, v253, 36
	s_mov_b64 s[14:15], s[2:3]
	s_mov_b64 s[16:17], s[34:35]
	v_lshl_or_b32 v176, s66, 7, v220
	v_lshlrev_b32_e32 v208, 2, v176
	s_lshl_b32 s34, s64, 8
	s_add_i32 s34, s34, s67
	s_lshr_b32 s35, s34, 4
	v_add_u32_e32 v209, s35, v217
	v_mul_u32_u24_e32 v209, 0x5800, v209
	v_add_u32_e32 v209, v209, v208
	v_or_b32_e32 v210, s34, v217
	v_mul_u32_u24_e32 v210, 0x1600, v210
	v_lshl_add_u32 v210, v176, 1, v210
	global_load_dwordx4 v[112:115], v208, s[24:25]
	global_load_dwordx4 v[116:119], v208, s[16:17]
	global_load_dwordx4 v[120:123], v208, s[30:31]
	global_load_dwordx4 v[124:127], v208, s[26:27]
	global_load_dwordx4 v[132:135], v208, s[14:15]
	global_load_dwordx4 v[136:139], v208, s[28:29]
	global_load_dwordx4 v[140:143], v208, s[40:41]
	global_load_dwordx4 v[144:147], v208, s[44:45]
	global_load_dwordx4 v[176:179], v208, s[24:25] offset:16
	global_load_dwordx4 v[180:183], v208, s[16:17] offset:16
	global_load_dwordx4 v[184:187], v208, s[30:31] offset:16
	global_load_dwordx4 v[188:191], v208, s[26:27] offset:16
	global_load_dwordx4 v[192:195], v208, s[14:15] offset:16
	global_load_dwordx4 v[196:199], v208, s[28:29] offset:16
	global_load_dwordx4 v[200:203], v208, s[40:41] offset:16
	global_load_dwordx4 v[204:207], v208, s[44:45] offset:16
	s_and_saveexec_b64 s[2:3], s[6:7]
	global_store_dwordx4 v209, v[156:159], s[38:39]
	global_store_dwordx4 v209, v[60:63], s[38:39] offset:16
	v_add_u32_e32 v211, 0x2c00, v209
	global_store_dwordx4 v211, v[152:155], s[38:39]
	global_store_dwordx4 v211, v[56:59], s[38:39] offset:16
	v_add_u32_e32 v211, 0x2c000, v209
	global_store_dwordx4 v211, v[92:95], s[38:39]
	global_store_dwordx4 v211, v[28:31], s[38:39] offset:16
	v_add_u32_e32 v211, 0x2ec00, v209
	global_store_dwordx4 v211, v[88:91], s[38:39]
	global_store_dwordx4 v211, v[24:27], s[38:39] offset:16
	s_or_b64 exec, exec, s[2:3]
	v_add_u32_e32 v212, 0xfffbe000, v209
	s_and_saveexec_b64 s[2:3], s[8:9]
	global_store_dwordx4 v212, v[100:103], s[38:39]
	global_store_dwordx4 v212, v[36:39], s[38:39] offset:16
	v_add_u32_e32 v211, 0x2c00, v212
	global_store_dwordx4 v211, v[96:99], s[38:39]
	global_store_dwordx4 v211, v[32:35], s[38:39] offset:16
	v_add_u32_e32 v211, 0x2c000, v212
	global_store_dwordx4 v211, v[68:71], s[38:39]
	global_store_dwordx4 v211, v[4:7], s[38:39] offset:16
	v_add_u32_e32 v211, 0x2ec00, v212
	global_store_dwordx4 v211, v[64:67], s[38:39]
	global_store_dwordx4 v211, v[0:3], s[38:39] offset:16
	s_or_b64 exec, exec, s[2:3]
	s_waitcnt vmcnt(16)
	v_fma_f32 v224, v116, v156, v124
	v_fma_f32 v225, v117, v157, v125
	v_fma_f32 v226, v118, v158, v126
	v_fma_f32 v227, v119, v159, v127
	v_fmac_f32_dpp v224, v156, v112 row_shr:1 row_mask:0xf bank_mask:0xf
	v_fmac_f32_dpp v225, v157, v113 row_shr:1 row_mask:0xf bank_mask:0xf
	v_fmac_f32_dpp v226, v158, v114 row_shr:1 row_mask:0xf bank_mask:0xf
	v_fmac_f32_dpp v227, v159, v115 row_shr:1 row_mask:0xf bank_mask:0xf
	v_fmac_f32_dpp v224, v156, v120 row_shl:1 row_mask:0xf bank_mask:0xf
	v_fmac_f32_dpp v225, v157, v121 row_shl:1 row_mask:0xf bank_mask:0xf
	v_fmac_f32_dpp v226, v158, v122 row_shl:1 row_mask:0xf bank_mask:0xf
	v_fmac_f32_dpp v227, v159, v123 row_shl:1 row_mask:0xf bank_mask:0xf
	v_fmac_f32_dpp v224, v148, v120 row_shr:15 row_mask:0xf bank_mask:0xf
	v_fmac_f32_dpp v225, v149, v121 row_shr:15 row_mask:0xf bank_mask:0xf
	v_fmac_f32_dpp v226, v150, v122 row_shr:15 row_mask:0xf bank_mask:0xf
	v_fmac_f32_dpp v227, v151, v123 row_shr:15 row_mask:0xf bank_mask:0xf
	v_fma_f32 v228, v136, v152, v144
	v_fma_f32 v229, v137, v153, v145
	v_fma_f32 v230, v138, v154, v146
	v_fma_f32 v231, v139, v155, v147
	v_fmac_f32_dpp v228, v152, v132 row_shr:1 row_mask:0xf bank_mask:0xf
	v_fmac_f32_dpp v229, v153, v133 row_shr:1 row_mask:0xf bank_mask:0xf
	v_fmac_f32_dpp v230, v154, v134 row_shr:1 row_mask:0xf bank_mask:0xf
	v_fmac_f32_dpp v231, v155, v135 row_shr:1 row_mask:0xf bank_mask:0xf
	v_fmac_f32_dpp v228, v152, v140 row_shl:1 row_mask:0xf bank_mask:0xf
	v_fmac_f32_dpp v229, v153, v141 row_shl:1 row_mask:0xf bank_mask:0xf
	v_fmac_f32_dpp v230, v154, v142 row_shl:1 row_mask:0xf bank_mask:0xf
	v_fmac_f32_dpp v231, v155, v143 row_shl:1 row_mask:0xf bank_mask:0xf
	v_fmac_f32_dpp v228, v128, v140 row_shr:15 row_mask:0xf bank_mask:0xf
	v_fmac_f32_dpp v229, v129, v141 row_shr:15 row_mask:0xf bank_mask:0xf
	v_fmac_f32_dpp v230, v130, v142 row_shr:15 row_mask:0xf bank_mask:0xf
	v_fmac_f32_dpp v231, v131, v143 row_shr:15 row_mask:0xf bank_mask:0xf
	v_mul_f32_e32 v232, 0xbfb8aa3b, v224
	v_mul_f32_e32 v233, 0xbfb8aa3b, v225
	v_mul_f32_e32 v234, 0xbfb8aa3b, v226
	v_mul_f32_e32 v235, 0xbfb8aa3b, v227
	v_exp_f32_e32 v232, v232
	v_exp_f32_e32 v233, v233
	v_exp_f32_e32 v234, v234
	v_exp_f32_e32 v235, v235
	v_add_f32_e32 v232, 1.0, v232
	v_add_f32_e32 v233, 1.0, v233
	v_add_f32_e32 v234, 1.0, v234
	v_add_f32_e32 v235, 1.0, v235
	v_rcp_f32_e32 v232, v232
	v_rcp_f32_e32 v233, v233
	v_rcp_f32_e32 v234, v234
	v_rcp_f32_e32 v235, v235
	v_mul_f32_e32 v224, v224, v232
	v_mul_f32_e32 v225, v225, v233
	v_mul_f32_e32 v226, v226, v234
	v_mul_f32_e32 v227, v227, v235
	v_mul_f32_e32 v224, v224, v228
	v_mul_f32_e32 v225, v225, v229
	v_mul_f32_e32 v226, v226, v230
	v_mul_f32_e32 v227, v227, v231
	v_cvt_pk_bf16_f32 v236, v224, v225
	v_cvt_pk_bf16_f32 v237, v226, v227
	global_store_dwordx2 v210, v[236:237], s[36:37]
	v_fma_f32 v224, v116, v148, v124
	v_fma_f32 v225, v117, v149, v125
	v_fma_f32 v226, v118, v150, v126
	v_fma_f32 v227, v119, v151, v127
	v_fmac_f32_dpp v224, v148, v112 row_shr:1 row_mask:0xf bank_mask:0xf
	v_fmac_f32_dpp v225, v149, v113 row_shr:1 row_mask:0xf bank_mask:0xf
	v_fmac_f32_dpp v226, v150, v114 row_shr:1 row_mask:0xf bank_mask:0xf
	v_fmac_f32_dpp v227, v151, v115 row_shr:1 row_mask:0xf bank_mask:0xf
	v_fmac_f32_dpp v224, v156, v112 row_shl:15 row_mask:0xf bank_mask:0xf
	v_fmac_f32_dpp v225, v157, v113 row_shl:15 row_mask:0xf bank_mask:0xf
	v_fmac_f32_dpp v226, v158, v114 row_shl:15 row_mask:0xf bank_mask:0xf
	v_fmac_f32_dpp v227, v159, v115 row_shl:15 row_mask:0xf bank_mask:0xf
	v_fmac_f32_dpp v224, v148, v120 row_shl:1 row_mask:0xf bank_mask:0xf
	v_fmac_f32_dpp v225, v149, v121 row_shl:1 row_mask:0xf bank_mask:0xf
	v_fmac_f32_dpp v226, v150, v122 row_shl:1 row_mask:0xf bank_mask:0xf
	v_fmac_f32_dpp v227, v151, v123 row_shl:1 row_mask:0xf bank_mask:0xf
	v_fmac_f32_dpp v224, v108, v120 row_shr:15 row_mask:0xf bank_mask:0xf
	v_fmac_f32_dpp v225, v109, v121 row_shr:15 row_mask:0xf bank_mask:0xf
	v_fmac_f32_dpp v226, v110, v122 row_shr:15 row_mask:0xf bank_mask:0xf
	v_fmac_f32_dpp v227, v111, v123 row_shr:15 row_mask:0xf bank_mask:0xf
	v_fma_f32 v228, v136, v128, v144
	v_fma_f32 v229, v137, v129, v145
	v_fma_f32 v230, v138, v130, v146
	v_fma_f32 v231, v139, v131, v147
	v_fmac_f32_dpp v228, v128, v132 row_shr:1 row_mask:0xf bank_mask:0xf
	v_fmac_f32_dpp v229, v129, v133 row_shr:1 row_mask:0xf bank_mask:0xf
	v_fmac_f32_dpp v230, v130, v134 row_shr:1 row_mask:0xf bank_mask:0xf
	v_fmac_f32_dpp v231, v131, v135 row_shr:1 row_mask:0xf bank_mask:0xf
	v_fmac_f32_dpp v228, v152, v132 row_shl:15 row_mask:0xf bank_mask:0xf
	v_fmac_f32_dpp v229, v153, v133 row_shl:15 row_mask:0xf bank_mask:0xf
	v_fmac_f32_dpp v230, v154, v134 row_shl:15 row_mask:0xf bank_mask:0xf
	v_fmac_f32_dpp v231, v155, v135 row_shl:15 row_mask:0xf bank_mask:0xf
	v_fmac_f32_dpp v228, v128, v140 row_shl:1 row_mask:0xf bank_mask:0xf
	v_fmac_f32_dpp v229, v129, v141 row_shl:1 row_mask:0xf bank_mask:0xf
	v_fmac_f32_dpp v230, v130, v142 row_shl:1 row_mask:0xf bank_mask:0xf
	v_fmac_f32_dpp v231, v131, v143 row_shl:1 row_mask:0xf bank_mask:0xf
	v_fmac_f32_dpp v228, v104, v140 row_shr:15 row_mask:0xf bank_mask:0xf
	v_fmac_f32_dpp v229, v105, v141 row_shr:15 row_mask:0xf bank_mask:0xf
	v_fmac_f32_dpp v230, v106, v142 row_shr:15 row_mask:0xf bank_mask:0xf
	v_fmac_f32_dpp v231, v107, v143 row_shr:15 row_mask:0xf bank_mask:0xf
	v_mul_f32_e32 v232, 0xbfb8aa3b, v224
	v_mul_f32_e32 v233, 0xbfb8aa3b, v225
	v_mul_f32_e32 v234, 0xbfb8aa3b, v226
	v_mul_f32_e32 v235, 0xbfb8aa3b, v227
	v_exp_f32_e32 v232, v232
	v_exp_f32_e32 v233, v233
	v_exp_f32_e32 v234, v234
	v_exp_f32_e32 v235, v235
	v_add_f32_e32 v232, 1.0, v232
	v_add_f32_e32 v233, 1.0, v233
	v_add_f32_e32 v234, 1.0, v234
	v_add_f32_e32 v235, 1.0, v235
	v_rcp_f32_e32 v232, v232
	v_rcp_f32_e32 v233, v233
	v_rcp_f32_e32 v234, v234
	v_rcp_f32_e32 v235, v235
	v_mul_f32_e32 v224, v224, v232
	v_mul_f32_e32 v225, v225, v233
	v_mul_f32_e32 v226, v226, v234
	v_mul_f32_e32 v227, v227, v235
	v_mul_f32_e32 v224, v224, v228
	v_mul_f32_e32 v225, v225, v229
	v_mul_f32_e32 v226, v226, v230
	v_mul_f32_e32 v227, v227, v231
	v_cvt_pk_bf16_f32 v236, v224, v225
	v_cvt_pk_bf16_f32 v237, v226, v227
	v_add_u32_e32 v213, 0x16000, v210
	global_store_dwordx2 v213, v[236:237], s[36:37]
	v_fma_f32 v224, v116, v108, v124
	v_fma_f32 v225, v117, v109, v125
	v_fma_f32 v226, v118, v110, v126
	v_fma_f32 v227, v119, v111, v127
	v_fmac_f32_dpp v224, v108, v112 row_shr:1 row_mask:0xf bank_mask:0xf
	v_fmac_f32_dpp v225, v109, v113 row_shr:1 row_mask:0xf bank_mask:0xf
	v_fmac_f32_dpp v226, v110, v114 row_shr:1 row_mask:0xf bank_mask:0xf
	v_fmac_f32_dpp v227, v111, v115 row_shr:1 row_mask:0xf bank_mask:0xf
	v_fmac_f32_dpp v224, v148, v112 row_shl:15 row_mask:0xf bank_mask:0xf
	v_fmac_f32_dpp v225, v149, v113 row_shl:15 row_mask:0xf bank_mask:0xf
	v_fmac_f32_dpp v226, v150, v114 row_shl:15 row_mask:0xf bank_mask:0xf
	v_fmac_f32_dpp v227, v151, v115 row_shl:15 row_mask:0xf bank_mask:0xf
	v_fmac_f32_dpp v224, v108, v120 row_shl:1 row_mask:0xf bank_mask:0xf
	v_fmac_f32_dpp v225, v109, v121 row_shl:1 row_mask:0xf bank_mask:0xf
	v_fmac_f32_dpp v226, v110, v122 row_shl:1 row_mask:0xf bank_mask:0xf
	v_fmac_f32_dpp v227, v111, v123 row_shl:1 row_mask:0xf bank_mask:0xf
	v_fmac_f32_dpp v224, v100, v120 row_shr:15 row_mask:0xf bank_mask:0xf
	v_fmac_f32_dpp v225, v101, v121 row_shr:15 row_mask:0xf bank_mask:0xf
	v_fmac_f32_dpp v226, v102, v122 row_shr:15 row_mask:0xf bank_mask:0xf
	v_fmac_f32_dpp v227, v103, v123 row_shr:15 row_mask:0xf bank_mask:0xf
	v_fma_f32 v228, v136, v104, v144
	v_fma_f32 v229, v137, v105, v145
	v_fma_f32 v230, v138, v106, v146
	v_fma_f32 v231, v139, v107, v147
	v_fmac_f32_dpp v228, v104, v132 row_shr:1 row_mask:0xf bank_mask:0xf
	v_fmac_f32_dpp v229, v105, v133 row_shr:1 row_mask:0xf bank_mask:0xf
	v_fmac_f32_dpp v230, v106, v134 row_shr:1 row_mask:0xf bank_mask:0xf
	v_fmac_f32_dpp v231, v107, v135 row_shr:1 row_mask:0xf bank_mask:0xf
	v_fmac_f32_dpp v228, v128, v132 row_shl:15 row_mask:0xf bank_mask:0xf
	v_fmac_f32_dpp v229, v129, v133 row_shl:15 row_mask:0xf bank_mask:0xf
	v_fmac_f32_dpp v230, v130, v134 row_shl:15 row_mask:0xf bank_mask:0xf
	v_fmac_f32_dpp v231, v131, v135 row_shl:15 row_mask:0xf bank_mask:0xf
	v_fmac_f32_dpp v228, v104, v140 row_shl:1 row_mask:0xf bank_mask:0xf
	v_fmac_f32_dpp v229, v105, v141 row_shl:1 row_mask:0xf bank_mask:0xf
	v_fmac_f32_dpp v230, v106, v142 row_shl:1 row_mask:0xf bank_mask:0xf
	v_fmac_f32_dpp v231, v107, v143 row_shl:1 row_mask:0xf bank_mask:0xf
	v_fmac_f32_dpp v228, v96, v140 row_shr:15 row_mask:0xf bank_mask:0xf
	v_fmac_f32_dpp v229, v97, v141 row_shr:15 row_mask:0xf bank_mask:0xf
	v_fmac_f32_dpp v230, v98, v142 row_shr:15 row_mask:0xf bank_mask:0xf
	v_fmac_f32_dpp v231, v99, v143 row_shr:15 row_mask:0xf bank_mask:0xf
	v_mul_f32_e32 v232, 0xbfb8aa3b, v224
	v_mul_f32_e32 v233, 0xbfb8aa3b, v225
	v_mul_f32_e32 v234, 0xbfb8aa3b, v226
	v_mul_f32_e32 v235, 0xbfb8aa3b, v227
	v_exp_f32_e32 v232, v232
	v_exp_f32_e32 v233, v233
	v_exp_f32_e32 v234, v234
	v_exp_f32_e32 v235, v235
	v_add_f32_e32 v232, 1.0, v232
	v_add_f32_e32 v233, 1.0, v233
	v_add_f32_e32 v234, 1.0, v234
	v_add_f32_e32 v235, 1.0, v235
	v_rcp_f32_e32 v232, v232
	v_rcp_f32_e32 v233, v233
	v_rcp_f32_e32 v234, v234
	v_rcp_f32_e32 v235, v235
	v_mul_f32_e32 v224, v224, v232
	v_mul_f32_e32 v225, v225, v233
	v_mul_f32_e32 v226, v226, v234
	v_mul_f32_e32 v227, v227, v235
	v_mul_f32_e32 v224, v224, v228
	v_mul_f32_e32 v225, v225, v229
	v_mul_f32_e32 v226, v226, v230
	v_mul_f32_e32 v227, v227, v231
	v_cvt_pk_bf16_f32 v236, v224, v225
	v_cvt_pk_bf16_f32 v237, v226, v227
	v_add_u32_e32 v213, 0x2c000, v210
	global_store_dwordx2 v213, v[236:237], s[36:37]
	v_fma_f32 v224, v116, v100, v124
	v_fma_f32 v225, v117, v101, v125
	v_fma_f32 v226, v118, v102, v126
	v_fma_f32 v227, v119, v103, v127
	v_fmac_f32_dpp v224, v100, v112 row_shr:1 row_mask:0xf bank_mask:0xf
	v_fmac_f32_dpp v225, v101, v113 row_shr:1 row_mask:0xf bank_mask:0xf
	v_fmac_f32_dpp v226, v102, v114 row_shr:1 row_mask:0xf bank_mask:0xf
	v_fmac_f32_dpp v227, v103, v115 row_shr:1 row_mask:0xf bank_mask:0xf
	v_fmac_f32_dpp v224, v108, v112 row_shl:15 row_mask:0xf bank_mask:0xf
	v_fmac_f32_dpp v225, v109, v113 row_shl:15 row_mask:0xf bank_mask:0xf
	v_fmac_f32_dpp v226, v110, v114 row_shl:15 row_mask:0xf bank_mask:0xf
	v_fmac_f32_dpp v227, v111, v115 row_shl:15 row_mask:0xf bank_mask:0xf
	v_fmac_f32_dpp v224, v100, v120 row_shl:1 row_mask:0xf bank_mask:0xf
	v_fmac_f32_dpp v225, v101, v121 row_shl:1 row_mask:0xf bank_mask:0xf
	v_fmac_f32_dpp v226, v102, v122 row_shl:1 row_mask:0xf bank_mask:0xf
	v_fmac_f32_dpp v227, v103, v123 row_shl:1 row_mask:0xf bank_mask:0xf
	v_fma_f32 v228, v136, v96, v144
	v_fma_f32 v229, v137, v97, v145
	v_fma_f32 v230, v138, v98, v146
	v_fma_f32 v231, v139, v99, v147
	v_fmac_f32_dpp v228, v96, v132 row_shr:1 row_mask:0xf bank_mask:0xf
	v_fmac_f32_dpp v229, v97, v133 row_shr:1 row_mask:0xf bank_mask:0xf
	v_fmac_f32_dpp v230, v98, v134 row_shr:1 row_mask:0xf bank_mask:0xf
	v_fmac_f32_dpp v231, v99, v135 row_shr:1 row_mask:0xf bank_mask:0xf
	v_fmac_f32_dpp v228, v104, v132 row_shl:15 row_mask:0xf bank_mask:0xf
	v_fmac_f32_dpp v229, v105, v133 row_shl:15 row_mask:0xf bank_mask:0xf
	v_fmac_f32_dpp v230, v106, v134 row_shl:15 row_mask:0xf bank_mask:0xf
	v_fmac_f32_dpp v231, v107, v135 row_shl:15 row_mask:0xf bank_mask:0xf
	v_fmac_f32_dpp v228, v96, v140 row_shl:1 row_mask:0xf bank_mask:0xf
	v_fmac_f32_dpp v229, v97, v141 row_shl:1 row_mask:0xf bank_mask:0xf
	v_fmac_f32_dpp v230, v98, v142 row_shl:1 row_mask:0xf bank_mask:0xf
	v_fmac_f32_dpp v231, v99, v143 row_shl:1 row_mask:0xf bank_mask:0xf
	v_mul_f32_e32 v232, 0xbfb8aa3b, v224
	v_mul_f32_e32 v233, 0xbfb8aa3b, v225
	v_mul_f32_e32 v234, 0xbfb8aa3b, v226
	v_mul_f32_e32 v235, 0xbfb8aa3b, v227
	v_exp_f32_e32 v232, v232
	v_exp_f32_e32 v233, v233
	v_exp_f32_e32 v234, v234
	v_exp_f32_e32 v235, v235
	v_add_f32_e32 v232, 1.0, v232
	v_add_f32_e32 v233, 1.0, v233
	v_add_f32_e32 v234, 1.0, v234
	v_add_f32_e32 v235, 1.0, v235
	v_rcp_f32_e32 v232, v232
	v_rcp_f32_e32 v233, v233
	v_rcp_f32_e32 v234, v234
	v_rcp_f32_e32 v235, v235
	v_mul_f32_e32 v224, v224, v232
	v_mul_f32_e32 v225, v225, v233
	v_mul_f32_e32 v226, v226, v234
	v_mul_f32_e32 v227, v227, v235
	v_mul_f32_e32 v224, v224, v228
	v_mul_f32_e32 v225, v225, v229
	v_mul_f32_e32 v226, v226, v230
	v_mul_f32_e32 v227, v227, v231
	v_cvt_pk_bf16_f32 v236, v224, v225
	v_cvt_pk_bf16_f32 v237, v226, v227
	v_add_u32_e32 v213, 0x42000, v210
	global_store_dwordx2 v213, v[236:237], s[36:37]
	v_fma_f32 v224, v116, v92, v124
	v_fma_f32 v225, v117, v93, v125
	v_fma_f32 v226, v118, v94, v126
	v_fma_f32 v227, v119, v95, v127
	v_fmac_f32_dpp v224, v92, v112 row_shr:1 row_mask:0xf bank_mask:0xf
	v_fmac_f32_dpp v225, v93, v113 row_shr:1 row_mask:0xf bank_mask:0xf
	v_fmac_f32_dpp v226, v94, v114 row_shr:1 row_mask:0xf bank_mask:0xf
	v_fmac_f32_dpp v227, v95, v115 row_shr:1 row_mask:0xf bank_mask:0xf
	v_fmac_f32_dpp v224, v92, v120 row_shl:1 row_mask:0xf bank_mask:0xf
	v_fmac_f32_dpp v225, v93, v121 row_shl:1 row_mask:0xf bank_mask:0xf
	v_fmac_f32_dpp v226, v94, v122 row_shl:1 row_mask:0xf bank_mask:0xf
	v_fmac_f32_dpp v227, v95, v123 row_shl:1 row_mask:0xf bank_mask:0xf
	v_fmac_f32_dpp v224, v84, v120 row_shr:15 row_mask:0xf bank_mask:0xf
	v_fmac_f32_dpp v225, v85, v121 row_shr:15 row_mask:0xf bank_mask:0xf
	v_fmac_f32_dpp v226, v86, v122 row_shr:15 row_mask:0xf bank_mask:0xf
	v_fmac_f32_dpp v227, v87, v123 row_shr:15 row_mask:0xf bank_mask:0xf
	v_fma_f32 v228, v136, v88, v144
	v_fma_f32 v229, v137, v89, v145
	v_fma_f32 v230, v138, v90, v146
	v_fma_f32 v231, v139, v91, v147
	v_fmac_f32_dpp v228, v88, v132 row_shr:1 row_mask:0xf bank_mask:0xf
	v_fmac_f32_dpp v229, v89, v133 row_shr:1 row_mask:0xf bank_mask:0xf
	v_fmac_f32_dpp v230, v90, v134 row_shr:1 row_mask:0xf bank_mask:0xf
	v_fmac_f32_dpp v231, v91, v135 row_shr:1 row_mask:0xf bank_mask:0xf
	v_fmac_f32_dpp v228, v88, v140 row_shl:1 row_mask:0xf bank_mask:0xf
	v_fmac_f32_dpp v229, v89, v141 row_shl:1 row_mask:0xf bank_mask:0xf
	v_fmac_f32_dpp v230, v90, v142 row_shl:1 row_mask:0xf bank_mask:0xf
	v_fmac_f32_dpp v231, v91, v143 row_shl:1 row_mask:0xf bank_mask:0xf
	v_fmac_f32_dpp v228, v80, v140 row_shr:15 row_mask:0xf bank_mask:0xf
	v_fmac_f32_dpp v229, v81, v141 row_shr:15 row_mask:0xf bank_mask:0xf
	v_fmac_f32_dpp v230, v82, v142 row_shr:15 row_mask:0xf bank_mask:0xf
	v_fmac_f32_dpp v231, v83, v143 row_shr:15 row_mask:0xf bank_mask:0xf
	v_mul_f32_e32 v232, 0xbfb8aa3b, v224
	v_mul_f32_e32 v233, 0xbfb8aa3b, v225
	v_mul_f32_e32 v234, 0xbfb8aa3b, v226
	v_mul_f32_e32 v235, 0xbfb8aa3b, v227
	v_exp_f32_e32 v232, v232
	v_exp_f32_e32 v233, v233
	v_exp_f32_e32 v234, v234
	v_exp_f32_e32 v235, v235
	v_add_f32_e32 v232, 1.0, v232
	v_add_f32_e32 v233, 1.0, v233
	v_add_f32_e32 v234, 1.0, v234
	v_add_f32_e32 v235, 1.0, v235
	v_rcp_f32_e32 v232, v232
	v_rcp_f32_e32 v233, v233
	v_rcp_f32_e32 v234, v234
	v_rcp_f32_e32 v235, v235
	v_mul_f32_e32 v224, v224, v232
	v_mul_f32_e32 v225, v225, v233
	v_mul_f32_e32 v226, v226, v234
	v_mul_f32_e32 v227, v227, v235
	v_mul_f32_e32 v224, v224, v228
	v_mul_f32_e32 v225, v225, v229
	v_mul_f32_e32 v226, v226, v230
	v_mul_f32_e32 v227, v227, v231
	v_cvt_pk_bf16_f32 v236, v224, v225
	v_cvt_pk_bf16_f32 v237, v226, v227
	v_add_u32_e32 v213, 0xb0000, v210
	global_store_dwordx2 v213, v[236:237], s[36:37]
	v_fma_f32 v224, v116, v84, v124
	v_fma_f32 v225, v117, v85, v125
	v_fma_f32 v226, v118, v86, v126
	v_fma_f32 v227, v119, v87, v127
	v_fmac_f32_dpp v224, v84, v112 row_shr:1 row_mask:0xf bank_mask:0xf
	v_fmac_f32_dpp v225, v85, v113 row_shr:1 row_mask:0xf bank_mask:0xf
	v_fmac_f32_dpp v226, v86, v114 row_shr:1 row_mask:0xf bank_mask:0xf
	v_fmac_f32_dpp v227, v87, v115 row_shr:1 row_mask:0xf bank_mask:0xf
	v_fmac_f32_dpp v224, v92, v112 row_shl:15 row_mask:0xf bank_mask:0xf
	v_fmac_f32_dpp v225, v93, v113 row_shl:15 row_mask:0xf bank_mask:0xf
	v_fmac_f32_dpp v226, v94, v114 row_shl:15 row_mask:0xf bank_mask:0xf
	v_fmac_f32_dpp v227, v95, v115 row_shl:15 row_mask:0xf bank_mask:0xf
	v_fmac_f32_dpp v224, v84, v120 row_shl:1 row_mask:0xf bank_mask:0xf
	v_fmac_f32_dpp v225, v85, v121 row_shl:1 row_mask:0xf bank_mask:0xf
	v_fmac_f32_dpp v226, v86, v122 row_shl:1 row_mask:0xf bank_mask:0xf
	v_fmac_f32_dpp v227, v87, v123 row_shl:1 row_mask:0xf bank_mask:0xf
	v_fmac_f32_dpp v224, v76, v120 row_shr:15 row_mask:0xf bank_mask:0xf
	v_fmac_f32_dpp v225, v77, v121 row_shr:15 row_mask:0xf bank_mask:0xf
	v_fmac_f32_dpp v226, v78, v122 row_shr:15 row_mask:0xf bank_mask:0xf
	v_fmac_f32_dpp v227, v79, v123 row_shr:15 row_mask:0xf bank_mask:0xf
	v_fma_f32 v228, v136, v80, v144
	v_fma_f32 v229, v137, v81, v145
	v_fma_f32 v230, v138, v82, v146
	v_fma_f32 v231, v139, v83, v147
	v_fmac_f32_dpp v228, v80, v132 row_shr:1 row_mask:0xf bank_mask:0xf
	v_fmac_f32_dpp v229, v81, v133 row_shr:1 row_mask:0xf bank_mask:0xf
	v_fmac_f32_dpp v230, v82, v134 row_shr:1 row_mask:0xf bank_mask:0xf
	v_fmac_f32_dpp v231, v83, v135 row_shr:1 row_mask:0xf bank_mask:0xf
	v_fmac_f32_dpp v228, v88, v132 row_shl:15 row_mask:0xf bank_mask:0xf
	v_fmac_f32_dpp v229, v89, v133 row_shl:15 row_mask:0xf bank_mask:0xf
	v_fmac_f32_dpp v230, v90, v134 row_shl:15 row_mask:0xf bank_mask:0xf
	v_fmac_f32_dpp v231, v91, v135 row_shl:15 row_mask:0xf bank_mask:0xf
	v_fmac_f32_dpp v228, v80, v140 row_shl:1 row_mask:0xf bank_mask:0xf
	v_fmac_f32_dpp v229, v81, v141 row_shl:1 row_mask:0xf bank_mask:0xf
	v_fmac_f32_dpp v230, v82, v142 row_shl:1 row_mask:0xf bank_mask:0xf
	v_fmac_f32_dpp v231, v83, v143 row_shl:1 row_mask:0xf bank_mask:0xf
	v_fmac_f32_dpp v228, v72, v140 row_shr:15 row_mask:0xf bank_mask:0xf
	v_fmac_f32_dpp v229, v73, v141 row_shr:15 row_mask:0xf bank_mask:0xf
	v_fmac_f32_dpp v230, v74, v142 row_shr:15 row_mask:0xf bank_mask:0xf
	v_fmac_f32_dpp v231, v75, v143 row_shr:15 row_mask:0xf bank_mask:0xf
	v_mul_f32_e32 v232, 0xbfb8aa3b, v224
	v_mul_f32_e32 v233, 0xbfb8aa3b, v225
	v_mul_f32_e32 v234, 0xbfb8aa3b, v226
	v_mul_f32_e32 v235, 0xbfb8aa3b, v227
	v_exp_f32_e32 v232, v232
	v_exp_f32_e32 v233, v233
	v_exp_f32_e32 v234, v234
	v_exp_f32_e32 v235, v235
	v_add_f32_e32 v232, 1.0, v232
	v_add_f32_e32 v233, 1.0, v233
	v_add_f32_e32 v234, 1.0, v234
	v_add_f32_e32 v235, 1.0, v235
	v_rcp_f32_e32 v232, v232
	v_rcp_f32_e32 v233, v233
	v_rcp_f32_e32 v234, v234
	v_rcp_f32_e32 v235, v235
	v_mul_f32_e32 v224, v224, v232
	v_mul_f32_e32 v225, v225, v233
	v_mul_f32_e32 v226, v226, v234
	v_mul_f32_e32 v227, v227, v235
	v_mul_f32_e32 v224, v224, v228
	v_mul_f32_e32 v225, v225, v229
	v_mul_f32_e32 v226, v226, v230
	v_mul_f32_e32 v227, v227, v231
	v_cvt_pk_bf16_f32 v236, v224, v225
	v_cvt_pk_bf16_f32 v237, v226, v227
	v_add_u32_e32 v213, 0xc6000, v210
	global_store_dwordx2 v213, v[236:237], s[36:37]
	v_fma_f32 v224, v116, v76, v124
	v_fma_f32 v225, v117, v77, v125
	v_fma_f32 v226, v118, v78, v126
	v_fma_f32 v227, v119, v79, v127
	v_fmac_f32_dpp v224, v76, v112 row_shr:1 row_mask:0xf bank_mask:0xf
	v_fmac_f32_dpp v225, v77, v113 row_shr:1 row_mask:0xf bank_mask:0xf
	v_fmac_f32_dpp v226, v78, v114 row_shr:1 row_mask:0xf bank_mask:0xf
	v_fmac_f32_dpp v227, v79, v115 row_shr:1 row_mask:0xf bank_mask:0xf
	v_fmac_f32_dpp v224, v84, v112 row_shl:15 row_mask:0xf bank_mask:0xf
	v_fmac_f32_dpp v225, v85, v113 row_shl:15 row_mask:0xf bank_mask:0xf
	v_fmac_f32_dpp v226, v86, v114 row_shl:15 row_mask:0xf bank_mask:0xf
	v_fmac_f32_dpp v227, v87, v115 row_shl:15 row_mask:0xf bank_mask:0xf
	v_fmac_f32_dpp v224, v76, v120 row_shl:1 row_mask:0xf bank_mask:0xf
	v_fmac_f32_dpp v225, v77, v121 row_shl:1 row_mask:0xf bank_mask:0xf
	v_fmac_f32_dpp v226, v78, v122 row_shl:1 row_mask:0xf bank_mask:0xf
	v_fmac_f32_dpp v227, v79, v123 row_shl:1 row_mask:0xf bank_mask:0xf
	v_fmac_f32_dpp v224, v68, v120 row_shr:15 row_mask:0xf bank_mask:0xf
	v_fmac_f32_dpp v225, v69, v121 row_shr:15 row_mask:0xf bank_mask:0xf
	v_fmac_f32_dpp v226, v70, v122 row_shr:15 row_mask:0xf bank_mask:0xf
	v_fmac_f32_dpp v227, v71, v123 row_shr:15 row_mask:0xf bank_mask:0xf
	v_fma_f32 v228, v136, v72, v144
	v_fma_f32 v229, v137, v73, v145
	v_fma_f32 v230, v138, v74, v146
	v_fma_f32 v231, v139, v75, v147
	v_fmac_f32_dpp v228, v72, v132 row_shr:1 row_mask:0xf bank_mask:0xf
	v_fmac_f32_dpp v229, v73, v133 row_shr:1 row_mask:0xf bank_mask:0xf
	v_fmac_f32_dpp v230, v74, v134 row_shr:1 row_mask:0xf bank_mask:0xf
	v_fmac_f32_dpp v231, v75, v135 row_shr:1 row_mask:0xf bank_mask:0xf
	v_fmac_f32_dpp v228, v80, v132 row_shl:15 row_mask:0xf bank_mask:0xf
	v_fmac_f32_dpp v229, v81, v133 row_shl:15 row_mask:0xf bank_mask:0xf
	v_fmac_f32_dpp v230, v82, v134 row_shl:15 row_mask:0xf bank_mask:0xf
	v_fmac_f32_dpp v231, v83, v135 row_shl:15 row_mask:0xf bank_mask:0xf
	v_fmac_f32_dpp v228, v72, v140 row_shl:1 row_mask:0xf bank_mask:0xf
	v_fmac_f32_dpp v229, v73, v141 row_shl:1 row_mask:0xf bank_mask:0xf
	v_fmac_f32_dpp v230, v74, v142 row_shl:1 row_mask:0xf bank_mask:0xf
	v_fmac_f32_dpp v231, v75, v143 row_shl:1 row_mask:0xf bank_mask:0xf
	v_fmac_f32_dpp v228, v64, v140 row_shr:15 row_mask:0xf bank_mask:0xf
	v_fmac_f32_dpp v229, v65, v141 row_shr:15 row_mask:0xf bank_mask:0xf
	v_fmac_f32_dpp v230, v66, v142 row_shr:15 row_mask:0xf bank_mask:0xf
	v_fmac_f32_dpp v231, v67, v143 row_shr:15 row_mask:0xf bank_mask:0xf
	v_mul_f32_e32 v232, 0xbfb8aa3b, v224
	v_mul_f32_e32 v233, 0xbfb8aa3b, v225
	v_mul_f32_e32 v234, 0xbfb8aa3b, v226
	v_mul_f32_e32 v235, 0xbfb8aa3b, v227
	v_exp_f32_e32 v232, v232
	v_exp_f32_e32 v233, v233
	v_exp_f32_e32 v234, v234
	v_exp_f32_e32 v235, v235
	v_add_f32_e32 v232, 1.0, v232
	v_add_f32_e32 v233, 1.0, v233
	v_add_f32_e32 v234, 1.0, v234
	v_add_f32_e32 v235, 1.0, v235
	v_rcp_f32_e32 v232, v232
	v_rcp_f32_e32 v233, v233
	v_rcp_f32_e32 v234, v234
	v_rcp_f32_e32 v235, v235
	v_mul_f32_e32 v224, v224, v232
	v_mul_f32_e32 v225, v225, v233
	v_mul_f32_e32 v226, v226, v234
	v_mul_f32_e32 v227, v227, v235
	v_mul_f32_e32 v224, v224, v228
	v_mul_f32_e32 v225, v225, v229
	v_mul_f32_e32 v226, v226, v230
	v_mul_f32_e32 v227, v227, v231
	v_cvt_pk_bf16_f32 v236, v224, v225
	v_cvt_pk_bf16_f32 v237, v226, v227
	v_add_u32_e32 v213, 0xdc000, v210
	global_store_dwordx2 v213, v[236:237], s[36:37]
	v_fma_f32 v224, v116, v68, v124
	v_fma_f32 v225, v117, v69, v125
	v_fma_f32 v226, v118, v70, v126
	v_fma_f32 v227, v119, v71, v127
	v_fmac_f32_dpp v224, v68, v112 row_shr:1 row_mask:0xf bank_mask:0xf
	v_fmac_f32_dpp v225, v69, v113 row_shr:1 row_mask:0xf bank_mask:0xf
	v_fmac_f32_dpp v226, v70, v114 row_shr:1 row_mask:0xf bank_mask:0xf
	v_fmac_f32_dpp v227, v71, v115 row_shr:1 row_mask:0xf bank_mask:0xf
	v_fmac_f32_dpp v224, v76, v112 row_shl:15 row_mask:0xf bank_mask:0xf
	v_fmac_f32_dpp v225, v77, v113 row_shl:15 row_mask:0xf bank_mask:0xf
	v_fmac_f32_dpp v226, v78, v114 row_shl:15 row_mask:0xf bank_mask:0xf
	v_fmac_f32_dpp v227, v79, v115 row_shl:15 row_mask:0xf bank_mask:0xf
	v_fmac_f32_dpp v224, v68, v120 row_shl:1 row_mask:0xf bank_mask:0xf
	v_fmac_f32_dpp v225, v69, v121 row_shl:1 row_mask:0xf bank_mask:0xf
	v_fmac_f32_dpp v226, v70, v122 row_shl:1 row_mask:0xf bank_mask:0xf
	v_fmac_f32_dpp v227, v71, v123 row_shl:1 row_mask:0xf bank_mask:0xf
	v_fma_f32 v228, v136, v64, v144
	v_fma_f32 v229, v137, v65, v145
	v_fma_f32 v230, v138, v66, v146
	v_fma_f32 v231, v139, v67, v147
	v_fmac_f32_dpp v228, v64, v132 row_shr:1 row_mask:0xf bank_mask:0xf
	v_fmac_f32_dpp v229, v65, v133 row_shr:1 row_mask:0xf bank_mask:0xf
	v_fmac_f32_dpp v230, v66, v134 row_shr:1 row_mask:0xf bank_mask:0xf
	v_fmac_f32_dpp v231, v67, v135 row_shr:1 row_mask:0xf bank_mask:0xf
	v_fmac_f32_dpp v228, v72, v132 row_shl:15 row_mask:0xf bank_mask:0xf
	v_fmac_f32_dpp v229, v73, v133 row_shl:15 row_mask:0xf bank_mask:0xf
	v_fmac_f32_dpp v230, v74, v134 row_shl:15 row_mask:0xf bank_mask:0xf
	v_fmac_f32_dpp v231, v75, v135 row_shl:15 row_mask:0xf bank_mask:0xf
	v_fmac_f32_dpp v228, v64, v140 row_shl:1 row_mask:0xf bank_mask:0xf
	v_fmac_f32_dpp v229, v65, v141 row_shl:1 row_mask:0xf bank_mask:0xf
	v_fmac_f32_dpp v230, v66, v142 row_shl:1 row_mask:0xf bank_mask:0xf
	v_fmac_f32_dpp v231, v67, v143 row_shl:1 row_mask:0xf bank_mask:0xf
	v_mul_f32_e32 v232, 0xbfb8aa3b, v224
	v_mul_f32_e32 v233, 0xbfb8aa3b, v225
	v_mul_f32_e32 v234, 0xbfb8aa3b, v226
	v_mul_f32_e32 v235, 0xbfb8aa3b, v227
	v_exp_f32_e32 v232, v232
	v_exp_f32_e32 v233, v233
	v_exp_f32_e32 v234, v234
	v_exp_f32_e32 v235, v235
	v_add_f32_e32 v232, 1.0, v232
	v_add_f32_e32 v233, 1.0, v233
	v_add_f32_e32 v234, 1.0, v234
	v_add_f32_e32 v235, 1.0, v235
	v_rcp_f32_e32 v232, v232
	v_rcp_f32_e32 v233, v233
	v_rcp_f32_e32 v234, v234
	v_rcp_f32_e32 v235, v235
	v_mul_f32_e32 v224, v224, v232
	v_mul_f32_e32 v225, v225, v233
	v_mul_f32_e32 v226, v226, v234
	v_mul_f32_e32 v227, v227, v235
	v_mul_f32_e32 v224, v224, v228
	v_mul_f32_e32 v225, v225, v229
	v_mul_f32_e32 v226, v226, v230
	v_mul_f32_e32 v227, v227, v231
	v_cvt_pk_bf16_f32 v236, v224, v225
	v_cvt_pk_bf16_f32 v237, v226, v227
	v_add_u32_e32 v213, 0xf2000, v210
	global_store_dwordx2 v213, v[236:237], s[36:37]
	v_fma_f32 v224, v180, v60, v188
	v_fma_f32 v225, v181, v61, v189
	v_fma_f32 v226, v182, v62, v190
	v_fma_f32 v227, v183, v63, v191
	v_fmac_f32_dpp v224, v60, v176 row_shr:1 row_mask:0xf bank_mask:0xf
	v_fmac_f32_dpp v225, v61, v177 row_shr:1 row_mask:0xf bank_mask:0xf
	v_fmac_f32_dpp v226, v62, v178 row_shr:1 row_mask:0xf bank_mask:0xf
	v_fmac_f32_dpp v227, v63, v179 row_shr:1 row_mask:0xf bank_mask:0xf
	v_fmac_f32_dpp v224, v60, v184 row_shl:1 row_mask:0xf bank_mask:0xf
	v_fmac_f32_dpp v225, v61, v185 row_shl:1 row_mask:0xf bank_mask:0xf
	v_fmac_f32_dpp v226, v62, v186 row_shl:1 row_mask:0xf bank_mask:0xf
	v_fmac_f32_dpp v227, v63, v187 row_shl:1 row_mask:0xf bank_mask:0xf
	v_fmac_f32_dpp v224, v52, v184 row_shr:15 row_mask:0xf bank_mask:0xf
	v_fmac_f32_dpp v225, v53, v185 row_shr:15 row_mask:0xf bank_mask:0xf
	v_fmac_f32_dpp v226, v54, v186 row_shr:15 row_mask:0xf bank_mask:0xf
	v_fmac_f32_dpp v227, v55, v187 row_shr:15 row_mask:0xf bank_mask:0xf
	v_fma_f32 v228, v196, v56, v204
	v_fma_f32 v229, v197, v57, v205
	v_fma_f32 v230, v198, v58, v206
	v_fma_f32 v231, v199, v59, v207
	v_fmac_f32_dpp v228, v56, v192 row_shr:1 row_mask:0xf bank_mask:0xf
	v_fmac_f32_dpp v229, v57, v193 row_shr:1 row_mask:0xf bank_mask:0xf
	v_fmac_f32_dpp v230, v58, v194 row_shr:1 row_mask:0xf bank_mask:0xf
	v_fmac_f32_dpp v231, v59, v195 row_shr:1 row_mask:0xf bank_mask:0xf
	v_fmac_f32_dpp v228, v56, v200 row_shl:1 row_mask:0xf bank_mask:0xf
	v_fmac_f32_dpp v229, v57, v201 row_shl:1 row_mask:0xf bank_mask:0xf
	v_fmac_f32_dpp v230, v58, v202 row_shl:1 row_mask:0xf bank_mask:0xf
	v_fmac_f32_dpp v231, v59, v203 row_shl:1 row_mask:0xf bank_mask:0xf
	v_fmac_f32_dpp v228, v48, v200 row_shr:15 row_mask:0xf bank_mask:0xf
	v_fmac_f32_dpp v229, v49, v201 row_shr:15 row_mask:0xf bank_mask:0xf
	v_fmac_f32_dpp v230, v50, v202 row_shr:15 row_mask:0xf bank_mask:0xf
	v_fmac_f32_dpp v231, v51, v203 row_shr:15 row_mask:0xf bank_mask:0xf
	v_mul_f32_e32 v232, 0xbfb8aa3b, v224
	v_mul_f32_e32 v233, 0xbfb8aa3b, v225
	v_mul_f32_e32 v234, 0xbfb8aa3b, v226
	v_mul_f32_e32 v235, 0xbfb8aa3b, v227
	v_exp_f32_e32 v232, v232
	v_exp_f32_e32 v233, v233
	v_exp_f32_e32 v234, v234
	v_exp_f32_e32 v235, v235
	v_add_f32_e32 v232, 1.0, v232
	v_add_f32_e32 v233, 1.0, v233
	v_add_f32_e32 v234, 1.0, v234
	v_add_f32_e32 v235, 1.0, v235
	v_rcp_f32_e32 v232, v232
	v_rcp_f32_e32 v233, v233
	v_rcp_f32_e32 v234, v234
	v_rcp_f32_e32 v235, v235
	v_mul_f32_e32 v224, v224, v232
	v_mul_f32_e32 v225, v225, v233
	v_mul_f32_e32 v226, v226, v234
	v_mul_f32_e32 v227, v227, v235
	v_mul_f32_e32 v224, v224, v228
	v_mul_f32_e32 v225, v225, v229
	v_mul_f32_e32 v226, v226, v230
	v_mul_f32_e32 v227, v227, v231
	v_cvt_pk_bf16_f32 v236, v224, v225
	v_cvt_pk_bf16_f32 v237, v226, v227
	global_store_dwordx2 v210, v[236:237], s[36:37] offset:8
	v_fma_f32 v224, v180, v52, v188
	v_fma_f32 v225, v181, v53, v189
	v_fma_f32 v226, v182, v54, v190
	v_fma_f32 v227, v183, v55, v191
	v_fmac_f32_dpp v224, v52, v176 row_shr:1 row_mask:0xf bank_mask:0xf
	v_fmac_f32_dpp v225, v53, v177 row_shr:1 row_mask:0xf bank_mask:0xf
	v_fmac_f32_dpp v226, v54, v178 row_shr:1 row_mask:0xf bank_mask:0xf
	v_fmac_f32_dpp v227, v55, v179 row_shr:1 row_mask:0xf bank_mask:0xf
	v_fmac_f32_dpp v224, v60, v176 row_shl:15 row_mask:0xf bank_mask:0xf
	v_fmac_f32_dpp v225, v61, v177 row_shl:15 row_mask:0xf bank_mask:0xf
	v_fmac_f32_dpp v226, v62, v178 row_shl:15 row_mask:0xf bank_mask:0xf
	v_fmac_f32_dpp v227, v63, v179 row_shl:15 row_mask:0xf bank_mask:0xf
	v_fmac_f32_dpp v224, v52, v184 row_shl:1 row_mask:0xf bank_mask:0xf
	v_fmac_f32_dpp v225, v53, v185 row_shl:1 row_mask:0xf bank_mask:0xf
	v_fmac_f32_dpp v226, v54, v186 row_shl:1 row_mask:0xf bank_mask:0xf
	v_fmac_f32_dpp v227, v55, v187 row_shl:1 row_mask:0xf bank_mask:0xf
	v_fmac_f32_dpp v224, v44, v184 row_shr:15 row_mask:0xf bank_mask:0xf
	v_fmac_f32_dpp v225, v45, v185 row_shr:15 row_mask:0xf bank_mask:0xf
	v_fmac_f32_dpp v226, v46, v186 row_shr:15 row_mask:0xf bank_mask:0xf
	v_fmac_f32_dpp v227, v47, v187 row_shr:15 row_mask:0xf bank_mask:0xf
	v_fma_f32 v228, v196, v48, v204
	v_fma_f32 v229, v197, v49, v205
	v_fma_f32 v230, v198, v50, v206
	v_fma_f32 v231, v199, v51, v207
	v_fmac_f32_dpp v228, v48, v192 row_shr:1 row_mask:0xf bank_mask:0xf
	v_fmac_f32_dpp v229, v49, v193 row_shr:1 row_mask:0xf bank_mask:0xf
	v_fmac_f32_dpp v230, v50, v194 row_shr:1 row_mask:0xf bank_mask:0xf
	v_fmac_f32_dpp v231, v51, v195 row_shr:1 row_mask:0xf bank_mask:0xf
	v_fmac_f32_dpp v228, v56, v192 row_shl:15 row_mask:0xf bank_mask:0xf
	v_fmac_f32_dpp v229, v57, v193 row_shl:15 row_mask:0xf bank_mask:0xf
	v_fmac_f32_dpp v230, v58, v194 row_shl:15 row_mask:0xf bank_mask:0xf
	v_fmac_f32_dpp v231, v59, v195 row_shl:15 row_mask:0xf bank_mask:0xf
	v_fmac_f32_dpp v228, v48, v200 row_shl:1 row_mask:0xf bank_mask:0xf
	v_fmac_f32_dpp v229, v49, v201 row_shl:1 row_mask:0xf bank_mask:0xf
	v_fmac_f32_dpp v230, v50, v202 row_shl:1 row_mask:0xf bank_mask:0xf
	v_fmac_f32_dpp v231, v51, v203 row_shl:1 row_mask:0xf bank_mask:0xf
	v_fmac_f32_dpp v228, v40, v200 row_shr:15 row_mask:0xf bank_mask:0xf
	v_fmac_f32_dpp v229, v41, v201 row_shr:15 row_mask:0xf bank_mask:0xf
	v_fmac_f32_dpp v230, v42, v202 row_shr:15 row_mask:0xf bank_mask:0xf
	v_fmac_f32_dpp v231, v43, v203 row_shr:15 row_mask:0xf bank_mask:0xf
	v_mul_f32_e32 v232, 0xbfb8aa3b, v224
	v_mul_f32_e32 v233, 0xbfb8aa3b, v225
	v_mul_f32_e32 v234, 0xbfb8aa3b, v226
	v_mul_f32_e32 v235, 0xbfb8aa3b, v227
	v_exp_f32_e32 v232, v232
	v_exp_f32_e32 v233, v233
	v_exp_f32_e32 v234, v234
	v_exp_f32_e32 v235, v235
	v_add_f32_e32 v232, 1.0, v232
	v_add_f32_e32 v233, 1.0, v233
	v_add_f32_e32 v234, 1.0, v234
	v_add_f32_e32 v235, 1.0, v235
	v_rcp_f32_e32 v232, v232
	v_rcp_f32_e32 v233, v233
	v_rcp_f32_e32 v234, v234
	v_rcp_f32_e32 v235, v235
	v_mul_f32_e32 v224, v224, v232
	v_mul_f32_e32 v225, v225, v233
	v_mul_f32_e32 v226, v226, v234
	v_mul_f32_e32 v227, v227, v235
	v_mul_f32_e32 v224, v224, v228
	v_mul_f32_e32 v225, v225, v229
	v_mul_f32_e32 v226, v226, v230
	v_mul_f32_e32 v227, v227, v231
	v_cvt_pk_bf16_f32 v236, v224, v225
	v_cvt_pk_bf16_f32 v237, v226, v227
	v_add_u32_e32 v213, 0x16000, v210
	global_store_dwordx2 v213, v[236:237], s[36:37] offset:8
	v_fma_f32 v224, v180, v44, v188
	v_fma_f32 v225, v181, v45, v189
	v_fma_f32 v226, v182, v46, v190
	v_fma_f32 v227, v183, v47, v191
	v_fmac_f32_dpp v224, v44, v176 row_shr:1 row_mask:0xf bank_mask:0xf
	v_fmac_f32_dpp v225, v45, v177 row_shr:1 row_mask:0xf bank_mask:0xf
	v_fmac_f32_dpp v226, v46, v178 row_shr:1 row_mask:0xf bank_mask:0xf
	v_fmac_f32_dpp v227, v47, v179 row_shr:1 row_mask:0xf bank_mask:0xf
	v_fmac_f32_dpp v224, v52, v176 row_shl:15 row_mask:0xf bank_mask:0xf
	v_fmac_f32_dpp v225, v53, v177 row_shl:15 row_mask:0xf bank_mask:0xf
	v_fmac_f32_dpp v226, v54, v178 row_shl:15 row_mask:0xf bank_mask:0xf
	v_fmac_f32_dpp v227, v55, v179 row_shl:15 row_mask:0xf bank_mask:0xf
	v_fmac_f32_dpp v224, v44, v184 row_shl:1 row_mask:0xf bank_mask:0xf
	v_fmac_f32_dpp v225, v45, v185 row_shl:1 row_mask:0xf bank_mask:0xf
	v_fmac_f32_dpp v226, v46, v186 row_shl:1 row_mask:0xf bank_mask:0xf
	v_fmac_f32_dpp v227, v47, v187 row_shl:1 row_mask:0xf bank_mask:0xf
	v_fmac_f32_dpp v224, v36, v184 row_shr:15 row_mask:0xf bank_mask:0xf
	v_fmac_f32_dpp v225, v37, v185 row_shr:15 row_mask:0xf bank_mask:0xf
	v_fmac_f32_dpp v226, v38, v186 row_shr:15 row_mask:0xf bank_mask:0xf
	v_fmac_f32_dpp v227, v39, v187 row_shr:15 row_mask:0xf bank_mask:0xf
	v_fma_f32 v228, v196, v40, v204
	v_fma_f32 v229, v197, v41, v205
	v_fma_f32 v230, v198, v42, v206
	v_fma_f32 v231, v199, v43, v207
	v_fmac_f32_dpp v228, v40, v192 row_shr:1 row_mask:0xf bank_mask:0xf
	v_fmac_f32_dpp v229, v41, v193 row_shr:1 row_mask:0xf bank_mask:0xf
	v_fmac_f32_dpp v230, v42, v194 row_shr:1 row_mask:0xf bank_mask:0xf
	v_fmac_f32_dpp v231, v43, v195 row_shr:1 row_mask:0xf bank_mask:0xf
	v_fmac_f32_dpp v228, v48, v192 row_shl:15 row_mask:0xf bank_mask:0xf
	v_fmac_f32_dpp v229, v49, v193 row_shl:15 row_mask:0xf bank_mask:0xf
	v_fmac_f32_dpp v230, v50, v194 row_shl:15 row_mask:0xf bank_mask:0xf
	v_fmac_f32_dpp v231, v51, v195 row_shl:15 row_mask:0xf bank_mask:0xf
	v_fmac_f32_dpp v228, v40, v200 row_shl:1 row_mask:0xf bank_mask:0xf
	v_fmac_f32_dpp v229, v41, v201 row_shl:1 row_mask:0xf bank_mask:0xf
	v_fmac_f32_dpp v230, v42, v202 row_shl:1 row_mask:0xf bank_mask:0xf
	v_fmac_f32_dpp v231, v43, v203 row_shl:1 row_mask:0xf bank_mask:0xf
	v_fmac_f32_dpp v228, v32, v200 row_shr:15 row_mask:0xf bank_mask:0xf
	v_fmac_f32_dpp v229, v33, v201 row_shr:15 row_mask:0xf bank_mask:0xf
	v_fmac_f32_dpp v230, v34, v202 row_shr:15 row_mask:0xf bank_mask:0xf
	v_fmac_f32_dpp v231, v35, v203 row_shr:15 row_mask:0xf bank_mask:0xf
	v_mul_f32_e32 v232, 0xbfb8aa3b, v224
	v_mul_f32_e32 v233, 0xbfb8aa3b, v225
	v_mul_f32_e32 v234, 0xbfb8aa3b, v226
	v_mul_f32_e32 v235, 0xbfb8aa3b, v227
	v_exp_f32_e32 v232, v232
	v_exp_f32_e32 v233, v233
	v_exp_f32_e32 v234, v234
	v_exp_f32_e32 v235, v235
	v_add_f32_e32 v232, 1.0, v232
	v_add_f32_e32 v233, 1.0, v233
	v_add_f32_e32 v234, 1.0, v234
	v_add_f32_e32 v235, 1.0, v235
	v_rcp_f32_e32 v232, v232
	v_rcp_f32_e32 v233, v233
	v_rcp_f32_e32 v234, v234
	v_rcp_f32_e32 v235, v235
	v_mul_f32_e32 v224, v224, v232
	v_mul_f32_e32 v225, v225, v233
	v_mul_f32_e32 v226, v226, v234
	v_mul_f32_e32 v227, v227, v235
	v_mul_f32_e32 v224, v224, v228
	v_mul_f32_e32 v225, v225, v229
	v_mul_f32_e32 v226, v226, v230
	v_mul_f32_e32 v227, v227, v231
	v_cvt_pk_bf16_f32 v236, v224, v225
	v_cvt_pk_bf16_f32 v237, v226, v227
	v_add_u32_e32 v213, 0x2c000, v210
	global_store_dwordx2 v213, v[236:237], s[36:37] offset:8
	v_fma_f32 v224, v180, v36, v188
	v_fma_f32 v225, v181, v37, v189
	v_fma_f32 v226, v182, v38, v190
	v_fma_f32 v227, v183, v39, v191
	v_fmac_f32_dpp v224, v36, v176 row_shr:1 row_mask:0xf bank_mask:0xf
	v_fmac_f32_dpp v225, v37, v177 row_shr:1 row_mask:0xf bank_mask:0xf
	v_fmac_f32_dpp v226, v38, v178 row_shr:1 row_mask:0xf bank_mask:0xf
	v_fmac_f32_dpp v227, v39, v179 row_shr:1 row_mask:0xf bank_mask:0xf
	v_fmac_f32_dpp v224, v44, v176 row_shl:15 row_mask:0xf bank_mask:0xf
	v_fmac_f32_dpp v225, v45, v177 row_shl:15 row_mask:0xf bank_mask:0xf
	v_fmac_f32_dpp v226, v46, v178 row_shl:15 row_mask:0xf bank_mask:0xf
	v_fmac_f32_dpp v227, v47, v179 row_shl:15 row_mask:0xf bank_mask:0xf
	v_fmac_f32_dpp v224, v36, v184 row_shl:1 row_mask:0xf bank_mask:0xf
	v_fmac_f32_dpp v225, v37, v185 row_shl:1 row_mask:0xf bank_mask:0xf
	v_fmac_f32_dpp v226, v38, v186 row_shl:1 row_mask:0xf bank_mask:0xf
	v_fmac_f32_dpp v227, v39, v187 row_shl:1 row_mask:0xf bank_mask:0xf
	v_fma_f32 v228, v196, v32, v204
	v_fma_f32 v229, v197, v33, v205
	v_fma_f32 v230, v198, v34, v206
	v_fma_f32 v231, v199, v35, v207
	v_fmac_f32_dpp v228, v32, v192 row_shr:1 row_mask:0xf bank_mask:0xf
	v_fmac_f32_dpp v229, v33, v193 row_shr:1 row_mask:0xf bank_mask:0xf
	v_fmac_f32_dpp v230, v34, v194 row_shr:1 row_mask:0xf bank_mask:0xf
	v_fmac_f32_dpp v231, v35, v195 row_shr:1 row_mask:0xf bank_mask:0xf
	v_fmac_f32_dpp v228, v40, v192 row_shl:15 row_mask:0xf bank_mask:0xf
	v_fmac_f32_dpp v229, v41, v193 row_shl:15 row_mask:0xf bank_mask:0xf
	v_fmac_f32_dpp v230, v42, v194 row_shl:15 row_mask:0xf bank_mask:0xf
	v_fmac_f32_dpp v231, v43, v195 row_shl:15 row_mask:0xf bank_mask:0xf
	v_fmac_f32_dpp v228, v32, v200 row_shl:1 row_mask:0xf bank_mask:0xf
	v_fmac_f32_dpp v229, v33, v201 row_shl:1 row_mask:0xf bank_mask:0xf
	v_fmac_f32_dpp v230, v34, v202 row_shl:1 row_mask:0xf bank_mask:0xf
	v_fmac_f32_dpp v231, v35, v203 row_shl:1 row_mask:0xf bank_mask:0xf
	v_mul_f32_e32 v232, 0xbfb8aa3b, v224
	v_mul_f32_e32 v233, 0xbfb8aa3b, v225
	v_mul_f32_e32 v234, 0xbfb8aa3b, v226
	v_mul_f32_e32 v235, 0xbfb8aa3b, v227
	v_exp_f32_e32 v232, v232
	v_exp_f32_e32 v233, v233
	v_exp_f32_e32 v234, v234
	v_exp_f32_e32 v235, v235
	v_add_f32_e32 v232, 1.0, v232
	v_add_f32_e32 v233, 1.0, v233
	v_add_f32_e32 v234, 1.0, v234
	v_add_f32_e32 v235, 1.0, v235
	v_rcp_f32_e32 v232, v232
	v_rcp_f32_e32 v233, v233
	v_rcp_f32_e32 v234, v234
	v_rcp_f32_e32 v235, v235
	v_mul_f32_e32 v224, v224, v232
	v_mul_f32_e32 v225, v225, v233
	v_mul_f32_e32 v226, v226, v234
	v_mul_f32_e32 v227, v227, v235
	v_mul_f32_e32 v224, v224, v228
	v_mul_f32_e32 v225, v225, v229
	v_mul_f32_e32 v226, v226, v230
	v_mul_f32_e32 v227, v227, v231
	v_cvt_pk_bf16_f32 v236, v224, v225
	v_cvt_pk_bf16_f32 v237, v226, v227
	v_add_u32_e32 v213, 0x42000, v210
	global_store_dwordx2 v213, v[236:237], s[36:37] offset:8
	v_fma_f32 v224, v180, v28, v188
	v_fma_f32 v225, v181, v29, v189
	v_fma_f32 v226, v182, v30, v190
	v_fma_f32 v227, v183, v31, v191
	v_fmac_f32_dpp v224, v28, v176 row_shr:1 row_mask:0xf bank_mask:0xf
	v_fmac_f32_dpp v225, v29, v177 row_shr:1 row_mask:0xf bank_mask:0xf
	v_fmac_f32_dpp v226, v30, v178 row_shr:1 row_mask:0xf bank_mask:0xf
	v_fmac_f32_dpp v227, v31, v179 row_shr:1 row_mask:0xf bank_mask:0xf
	v_fmac_f32_dpp v224, v28, v184 row_shl:1 row_mask:0xf bank_mask:0xf
	v_fmac_f32_dpp v225, v29, v185 row_shl:1 row_mask:0xf bank_mask:0xf
	v_fmac_f32_dpp v226, v30, v186 row_shl:1 row_mask:0xf bank_mask:0xf
	v_fmac_f32_dpp v227, v31, v187 row_shl:1 row_mask:0xf bank_mask:0xf
	v_fmac_f32_dpp v224, v20, v184 row_shr:15 row_mask:0xf bank_mask:0xf
	v_fmac_f32_dpp v225, v21, v185 row_shr:15 row_mask:0xf bank_mask:0xf
	v_fmac_f32_dpp v226, v22, v186 row_shr:15 row_mask:0xf bank_mask:0xf
	v_fmac_f32_dpp v227, v23, v187 row_shr:15 row_mask:0xf bank_mask:0xf
	v_fma_f32 v228, v196, v24, v204
	v_fma_f32 v229, v197, v25, v205
	v_fma_f32 v230, v198, v26, v206
	v_fma_f32 v231, v199, v27, v207
	v_fmac_f32_dpp v228, v24, v192 row_shr:1 row_mask:0xf bank_mask:0xf
	v_fmac_f32_dpp v229, v25, v193 row_shr:1 row_mask:0xf bank_mask:0xf
	v_fmac_f32_dpp v230, v26, v194 row_shr:1 row_mask:0xf bank_mask:0xf
	v_fmac_f32_dpp v231, v27, v195 row_shr:1 row_mask:0xf bank_mask:0xf
	v_fmac_f32_dpp v228, v24, v200 row_shl:1 row_mask:0xf bank_mask:0xf
	v_fmac_f32_dpp v229, v25, v201 row_shl:1 row_mask:0xf bank_mask:0xf
	v_fmac_f32_dpp v230, v26, v202 row_shl:1 row_mask:0xf bank_mask:0xf
	v_fmac_f32_dpp v231, v27, v203 row_shl:1 row_mask:0xf bank_mask:0xf
	v_fmac_f32_dpp v228, v16, v200 row_shr:15 row_mask:0xf bank_mask:0xf
	v_fmac_f32_dpp v229, v17, v201 row_shr:15 row_mask:0xf bank_mask:0xf
	v_fmac_f32_dpp v230, v18, v202 row_shr:15 row_mask:0xf bank_mask:0xf
	v_fmac_f32_dpp v231, v19, v203 row_shr:15 row_mask:0xf bank_mask:0xf
	v_mul_f32_e32 v232, 0xbfb8aa3b, v224
	v_mul_f32_e32 v233, 0xbfb8aa3b, v225
	v_mul_f32_e32 v234, 0xbfb8aa3b, v226
	v_mul_f32_e32 v235, 0xbfb8aa3b, v227
	v_exp_f32_e32 v232, v232
	v_exp_f32_e32 v233, v233
	v_exp_f32_e32 v234, v234
	v_exp_f32_e32 v235, v235
	v_add_f32_e32 v232, 1.0, v232
	v_add_f32_e32 v233, 1.0, v233
	v_add_f32_e32 v234, 1.0, v234
	v_add_f32_e32 v235, 1.0, v235
	v_rcp_f32_e32 v232, v232
	v_rcp_f32_e32 v233, v233
	v_rcp_f32_e32 v234, v234
	v_rcp_f32_e32 v235, v235
	v_mul_f32_e32 v224, v224, v232
	v_mul_f32_e32 v225, v225, v233
	v_mul_f32_e32 v226, v226, v234
	v_mul_f32_e32 v227, v227, v235
	v_mul_f32_e32 v224, v224, v228
	v_mul_f32_e32 v225, v225, v229
	v_mul_f32_e32 v226, v226, v230
	v_mul_f32_e32 v227, v227, v231
	v_cvt_pk_bf16_f32 v236, v224, v225
	v_cvt_pk_bf16_f32 v237, v226, v227
	v_add_u32_e32 v213, 0xb0000, v210
	global_store_dwordx2 v213, v[236:237], s[36:37] offset:8
	v_fma_f32 v224, v180, v20, v188
	v_fma_f32 v225, v181, v21, v189
	v_fma_f32 v226, v182, v22, v190
	v_fma_f32 v227, v183, v23, v191
	v_fmac_f32_dpp v224, v20, v176 row_shr:1 row_mask:0xf bank_mask:0xf
	v_fmac_f32_dpp v225, v21, v177 row_shr:1 row_mask:0xf bank_mask:0xf
	v_fmac_f32_dpp v226, v22, v178 row_shr:1 row_mask:0xf bank_mask:0xf
	v_fmac_f32_dpp v227, v23, v179 row_shr:1 row_mask:0xf bank_mask:0xf
	v_fmac_f32_dpp v224, v28, v176 row_shl:15 row_mask:0xf bank_mask:0xf
	v_fmac_f32_dpp v225, v29, v177 row_shl:15 row_mask:0xf bank_mask:0xf
	v_fmac_f32_dpp v226, v30, v178 row_shl:15 row_mask:0xf bank_mask:0xf
	v_fmac_f32_dpp v227, v31, v179 row_shl:15 row_mask:0xf bank_mask:0xf
	v_fmac_f32_dpp v224, v20, v184 row_shl:1 row_mask:0xf bank_mask:0xf
	v_fmac_f32_dpp v225, v21, v185 row_shl:1 row_mask:0xf bank_mask:0xf
	v_fmac_f32_dpp v226, v22, v186 row_shl:1 row_mask:0xf bank_mask:0xf
	v_fmac_f32_dpp v227, v23, v187 row_shl:1 row_mask:0xf bank_mask:0xf
	v_fmac_f32_dpp v224, v12, v184 row_shr:15 row_mask:0xf bank_mask:0xf
	v_fmac_f32_dpp v225, v13, v185 row_shr:15 row_mask:0xf bank_mask:0xf
	v_fmac_f32_dpp v226, v14, v186 row_shr:15 row_mask:0xf bank_mask:0xf
	v_fmac_f32_dpp v227, v15, v187 row_shr:15 row_mask:0xf bank_mask:0xf
	v_fma_f32 v228, v196, v16, v204
	v_fma_f32 v229, v197, v17, v205
	v_fma_f32 v230, v198, v18, v206
	v_fma_f32 v231, v199, v19, v207
	v_fmac_f32_dpp v228, v16, v192 row_shr:1 row_mask:0xf bank_mask:0xf
	v_fmac_f32_dpp v229, v17, v193 row_shr:1 row_mask:0xf bank_mask:0xf
	v_fmac_f32_dpp v230, v18, v194 row_shr:1 row_mask:0xf bank_mask:0xf
	v_fmac_f32_dpp v231, v19, v195 row_shr:1 row_mask:0xf bank_mask:0xf
	v_fmac_f32_dpp v228, v24, v192 row_shl:15 row_mask:0xf bank_mask:0xf
	v_fmac_f32_dpp v229, v25, v193 row_shl:15 row_mask:0xf bank_mask:0xf
	v_fmac_f32_dpp v230, v26, v194 row_shl:15 row_mask:0xf bank_mask:0xf
	v_fmac_f32_dpp v231, v27, v195 row_shl:15 row_mask:0xf bank_mask:0xf
	v_fmac_f32_dpp v228, v16, v200 row_shl:1 row_mask:0xf bank_mask:0xf
	v_fmac_f32_dpp v229, v17, v201 row_shl:1 row_mask:0xf bank_mask:0xf
	v_fmac_f32_dpp v230, v18, v202 row_shl:1 row_mask:0xf bank_mask:0xf
	v_fmac_f32_dpp v231, v19, v203 row_shl:1 row_mask:0xf bank_mask:0xf
	v_fmac_f32_dpp v228, v8, v200 row_shr:15 row_mask:0xf bank_mask:0xf
	v_fmac_f32_dpp v229, v9, v201 row_shr:15 row_mask:0xf bank_mask:0xf
	v_fmac_f32_dpp v230, v10, v202 row_shr:15 row_mask:0xf bank_mask:0xf
	v_fmac_f32_dpp v231, v11, v203 row_shr:15 row_mask:0xf bank_mask:0xf
	v_mul_f32_e32 v232, 0xbfb8aa3b, v224
	v_mul_f32_e32 v233, 0xbfb8aa3b, v225
	v_mul_f32_e32 v234, 0xbfb8aa3b, v226
	v_mul_f32_e32 v235, 0xbfb8aa3b, v227
	v_exp_f32_e32 v232, v232
	v_exp_f32_e32 v233, v233
	v_exp_f32_e32 v234, v234
	v_exp_f32_e32 v235, v235
	v_add_f32_e32 v232, 1.0, v232
	v_add_f32_e32 v233, 1.0, v233
	v_add_f32_e32 v234, 1.0, v234
	v_add_f32_e32 v235, 1.0, v235
	v_rcp_f32_e32 v232, v232
	v_rcp_f32_e32 v233, v233
	v_rcp_f32_e32 v234, v234
	v_rcp_f32_e32 v235, v235
	v_mul_f32_e32 v224, v224, v232
	v_mul_f32_e32 v225, v225, v233
	v_mul_f32_e32 v226, v226, v234
	v_mul_f32_e32 v227, v227, v235
	v_mul_f32_e32 v224, v224, v228
	v_mul_f32_e32 v225, v225, v229
	v_mul_f32_e32 v226, v226, v230
	v_mul_f32_e32 v227, v227, v231
	v_cvt_pk_bf16_f32 v236, v224, v225
	v_cvt_pk_bf16_f32 v237, v226, v227
	v_add_u32_e32 v213, 0xc6000, v210
	global_store_dwordx2 v213, v[236:237], s[36:37] offset:8
	v_fma_f32 v224, v180, v12, v188
	v_fma_f32 v225, v181, v13, v189
	v_fma_f32 v226, v182, v14, v190
	v_fma_f32 v227, v183, v15, v191
	v_fmac_f32_dpp v224, v12, v176 row_shr:1 row_mask:0xf bank_mask:0xf
	v_fmac_f32_dpp v225, v13, v177 row_shr:1 row_mask:0xf bank_mask:0xf
	v_fmac_f32_dpp v226, v14, v178 row_shr:1 row_mask:0xf bank_mask:0xf
	v_fmac_f32_dpp v227, v15, v179 row_shr:1 row_mask:0xf bank_mask:0xf
	v_fmac_f32_dpp v224, v20, v176 row_shl:15 row_mask:0xf bank_mask:0xf
	v_fmac_f32_dpp v225, v21, v177 row_shl:15 row_mask:0xf bank_mask:0xf
	v_fmac_f32_dpp v226, v22, v178 row_shl:15 row_mask:0xf bank_mask:0xf
	v_fmac_f32_dpp v227, v23, v179 row_shl:15 row_mask:0xf bank_mask:0xf
	v_fmac_f32_dpp v224, v12, v184 row_shl:1 row_mask:0xf bank_mask:0xf
	v_fmac_f32_dpp v225, v13, v185 row_shl:1 row_mask:0xf bank_mask:0xf
	v_fmac_f32_dpp v226, v14, v186 row_shl:1 row_mask:0xf bank_mask:0xf
	v_fmac_f32_dpp v227, v15, v187 row_shl:1 row_mask:0xf bank_mask:0xf
	v_fmac_f32_dpp v224, v4, v184 row_shr:15 row_mask:0xf bank_mask:0xf
	v_fmac_f32_dpp v225, v5, v185 row_shr:15 row_mask:0xf bank_mask:0xf
	v_fmac_f32_dpp v226, v6, v186 row_shr:15 row_mask:0xf bank_mask:0xf
	v_fmac_f32_dpp v227, v7, v187 row_shr:15 row_mask:0xf bank_mask:0xf
	v_fma_f32 v228, v196, v8, v204
	v_fma_f32 v229, v197, v9, v205
	v_fma_f32 v230, v198, v10, v206
	v_fma_f32 v231, v199, v11, v207
	v_fmac_f32_dpp v228, v8, v192 row_shr:1 row_mask:0xf bank_mask:0xf
	v_fmac_f32_dpp v229, v9, v193 row_shr:1 row_mask:0xf bank_mask:0xf
	v_fmac_f32_dpp v230, v10, v194 row_shr:1 row_mask:0xf bank_mask:0xf
	v_fmac_f32_dpp v231, v11, v195 row_shr:1 row_mask:0xf bank_mask:0xf
	v_fmac_f32_dpp v228, v16, v192 row_shl:15 row_mask:0xf bank_mask:0xf
	v_fmac_f32_dpp v229, v17, v193 row_shl:15 row_mask:0xf bank_mask:0xf
	v_fmac_f32_dpp v230, v18, v194 row_shl:15 row_mask:0xf bank_mask:0xf
	v_fmac_f32_dpp v231, v19, v195 row_shl:15 row_mask:0xf bank_mask:0xf
	v_fmac_f32_dpp v228, v8, v200 row_shl:1 row_mask:0xf bank_mask:0xf
	v_fmac_f32_dpp v229, v9, v201 row_shl:1 row_mask:0xf bank_mask:0xf
	v_fmac_f32_dpp v230, v10, v202 row_shl:1 row_mask:0xf bank_mask:0xf
	v_fmac_f32_dpp v231, v11, v203 row_shl:1 row_mask:0xf bank_mask:0xf
	v_fmac_f32_dpp v228, v0, v200 row_shr:15 row_mask:0xf bank_mask:0xf
	v_fmac_f32_dpp v229, v1, v201 row_shr:15 row_mask:0xf bank_mask:0xf
	v_fmac_f32_dpp v230, v2, v202 row_shr:15 row_mask:0xf bank_mask:0xf
	v_fmac_f32_dpp v231, v3, v203 row_shr:15 row_mask:0xf bank_mask:0xf
	v_mul_f32_e32 v232, 0xbfb8aa3b, v224
	v_mul_f32_e32 v233, 0xbfb8aa3b, v225
	v_mul_f32_e32 v234, 0xbfb8aa3b, v226
	v_mul_f32_e32 v235, 0xbfb8aa3b, v227
	v_exp_f32_e32 v232, v232
	v_exp_f32_e32 v233, v233
	v_exp_f32_e32 v234, v234
	v_exp_f32_e32 v235, v235
	v_add_f32_e32 v232, 1.0, v232
	v_add_f32_e32 v233, 1.0, v233
	v_add_f32_e32 v234, 1.0, v234
	v_add_f32_e32 v235, 1.0, v235
	v_rcp_f32_e32 v232, v232
	v_rcp_f32_e32 v233, v233
	v_rcp_f32_e32 v234, v234
	v_rcp_f32_e32 v235, v235
	v_mul_f32_e32 v224, v224, v232
	v_mul_f32_e32 v225, v225, v233
	v_mul_f32_e32 v226, v226, v234
	v_mul_f32_e32 v227, v227, v235
	v_mul_f32_e32 v224, v224, v228
	v_mul_f32_e32 v225, v225, v229
	v_mul_f32_e32 v226, v226, v230
	v_mul_f32_e32 v227, v227, v231
	v_cvt_pk_bf16_f32 v236, v224, v225
	v_cvt_pk_bf16_f32 v237, v226, v227
	v_add_u32_e32 v213, 0xdc000, v210
	global_store_dwordx2 v213, v[236:237], s[36:37] offset:8
	v_fma_f32 v224, v180, v4, v188
	v_fma_f32 v225, v181, v5, v189
	v_fma_f32 v226, v182, v6, v190
	v_fma_f32 v227, v183, v7, v191
	v_fmac_f32_dpp v224, v4, v176 row_shr:1 row_mask:0xf bank_mask:0xf
	v_fmac_f32_dpp v225, v5, v177 row_shr:1 row_mask:0xf bank_mask:0xf
	v_fmac_f32_dpp v226, v6, v178 row_shr:1 row_mask:0xf bank_mask:0xf
	v_fmac_f32_dpp v227, v7, v179 row_shr:1 row_mask:0xf bank_mask:0xf
	v_fmac_f32_dpp v224, v12, v176 row_shl:15 row_mask:0xf bank_mask:0xf
	v_fmac_f32_dpp v225, v13, v177 row_shl:15 row_mask:0xf bank_mask:0xf
	v_fmac_f32_dpp v226, v14, v178 row_shl:15 row_mask:0xf bank_mask:0xf
	v_fmac_f32_dpp v227, v15, v179 row_shl:15 row_mask:0xf bank_mask:0xf
	v_fmac_f32_dpp v224, v4, v184 row_shl:1 row_mask:0xf bank_mask:0xf
	v_fmac_f32_dpp v225, v5, v185 row_shl:1 row_mask:0xf bank_mask:0xf
	v_fmac_f32_dpp v226, v6, v186 row_shl:1 row_mask:0xf bank_mask:0xf
	v_fmac_f32_dpp v227, v7, v187 row_shl:1 row_mask:0xf bank_mask:0xf
	v_fma_f32 v228, v196, v0, v204
	v_fma_f32 v229, v197, v1, v205
	v_fma_f32 v230, v198, v2, v206
	v_fma_f32 v231, v199, v3, v207
	v_fmac_f32_dpp v228, v0, v192 row_shr:1 row_mask:0xf bank_mask:0xf
	v_fmac_f32_dpp v229, v1, v193 row_shr:1 row_mask:0xf bank_mask:0xf
	v_fmac_f32_dpp v230, v2, v194 row_shr:1 row_mask:0xf bank_mask:0xf
	v_fmac_f32_dpp v231, v3, v195 row_shr:1 row_mask:0xf bank_mask:0xf
	v_fmac_f32_dpp v228, v8, v192 row_shl:15 row_mask:0xf bank_mask:0xf
	v_fmac_f32_dpp v229, v9, v193 row_shl:15 row_mask:0xf bank_mask:0xf
	v_fmac_f32_dpp v230, v10, v194 row_shl:15 row_mask:0xf bank_mask:0xf
	v_fmac_f32_dpp v231, v11, v195 row_shl:15 row_mask:0xf bank_mask:0xf
	v_fmac_f32_dpp v228, v0, v200 row_shl:1 row_mask:0xf bank_mask:0xf
	v_fmac_f32_dpp v229, v1, v201 row_shl:1 row_mask:0xf bank_mask:0xf
	v_fmac_f32_dpp v230, v2, v202 row_shl:1 row_mask:0xf bank_mask:0xf
	v_fmac_f32_dpp v231, v3, v203 row_shl:1 row_mask:0xf bank_mask:0xf
	v_mul_f32_e32 v232, 0xbfb8aa3b, v224
	v_mul_f32_e32 v233, 0xbfb8aa3b, v225
	v_mul_f32_e32 v234, 0xbfb8aa3b, v226
	v_mul_f32_e32 v235, 0xbfb8aa3b, v227
	v_exp_f32_e32 v232, v232
	v_exp_f32_e32 v233, v233
	v_exp_f32_e32 v234, v234
	v_exp_f32_e32 v235, v235
	v_add_f32_e32 v232, 1.0, v232
	v_add_f32_e32 v233, 1.0, v233
	v_add_f32_e32 v234, 1.0, v234
	v_add_f32_e32 v235, 1.0, v235
	v_rcp_f32_e32 v232, v232
	v_rcp_f32_e32 v233, v233
	v_rcp_f32_e32 v234, v234
	v_rcp_f32_e32 v235, v235
	v_mul_f32_e32 v224, v224, v232
	v_mul_f32_e32 v225, v225, v233
	v_mul_f32_e32 v226, v226, v234
	v_mul_f32_e32 v227, v227, v235
	v_mul_f32_e32 v224, v224, v228
	v_mul_f32_e32 v225, v225, v229
	v_mul_f32_e32 v226, v226, v230
	v_mul_f32_e32 v227, v227, v231
	v_cvt_pk_bf16_f32 v236, v224, v225
	v_cvt_pk_bf16_f32 v237, v226, v227
	v_add_u32_e32 v213, 0xf2000, v210
	global_store_dwordx2 v213, v[236:237], s[36:37] offset:8
	s_andn2_b64 vcc, exec, s[10:11]
	s_mov_b64 s[2:3], -1
	s_cbranch_vccnz .LBB0_1180
	s_andn2_b64 vcc, exec, s[96:97]
	s_cbranch_vccnz .LBB0_1179
	s_barrier
	s_branch .LBB0_1179
